# k24: k22 + S2 first conv task: its five late own-row loads (rows 3..7) issued with the first batch instead of after the decay wait (one exposed round trip removed per unit)
# baseline (speedup 1.0000x reference)
.LBB0_1377:
	s_or_b64 exec, exec, s[2:3]
	s_or_b32 s2, s0, 0x7f
	s_ashr_i32 s3, s2, 31
	s_lshl_b32 s39, s63, 2
	s_lshl_b64 s[2:3], s[2:3], 7
	s_add_u32 s40, s18, s2
	s_addc_u32 s41, s19, s3
	s_ashr_i32 s2, s0, 6
	v_add_u32_e32 v22, s0, v150
	v_mov_b32_e32 v5, v121
	v_or_b32_e32 v18, s39, v151
	s_ashr_i32 s3, s2, 31
	v_ashrrev_i32_e32 v23, 31, v22
	v_lshl_add_u64 v[128:129], v[2:3], 0, v[4:5]
	v_lshlrev_b32_e32 v25, 2, v18
	s_lshl_b64 s[2:3], s[2:3], 7
	v_lshlrev_b64 v[26:27], 7, v[22:23]
	v_add_co_u32_e32 v2, vcc, 0x2000, v128
	s_add_u32 s42, s48, s2
	v_or_b32_e32 v26, v26, v25
	v_addc_co_u32_e32 v3, vcc, 0, v129, vcc
	s_addc_u32 s43, s49, s3
	v_lshl_add_u64 v[28:29], s[18:19], 0, v[26:27]
	global_load_dwordx4 v[74:77], v[2:3], off
	global_load_dword v18, v25, s[40:41]
	global_load_dword v21, v[28:29], off
	global_load_dword v20, v25, s[42:43]
	v_lshl_add_u64 v[26:27], s[16:17], 0, v[26:27]
	v_add_co_u32_e32 v2, vcc, s58, v128
	global_load_dwordx4 v[82:85], v[128:129], off
	s_nop 0
	v_addc_co_u32_e32 v3, vcc, 0, v129, vcc
	global_load_dwordx4 v[58:61], v[2:3], off
	s_mov_b32 s1, 0xa000
	v_add_co_u32_e32 v2, vcc, 0x6000, v128
	s_nop 1
	v_addc_co_u32_e32 v3, vcc, 0, v129, vcc
	global_load_dwordx4 v[38:41], v[2:3], off
	v_add_co_u32_e32 v2, vcc, 0x8000, v128
	s_nop 1
	v_addc_co_u32_e32 v3, vcc, 0, v129, vcc
	global_load_dwordx4 v[14:17], v[2:3], off
	v_add_co_u32_e32 v2, vcc, 0xa000, v128
	s_nop 1
	v_addc_co_u32_e32 v3, vcc, 0, v129, vcc
	global_load_dwordx4 v[10:13], v[2:3], off
	v_add_co_u32_e32 v2, vcc, 0xc000, v128
	s_nop 1
	v_addc_co_u32_e32 v3, vcc, 0, v129, vcc
	global_load_dwordx4 v[6:9], v[2:3], off
	v_add_co_u32_e32 v2, vcc, 0xe000, v128
	s_nop 1
	v_addc_co_u32_e32 v3, vcc, 0, v129, vcc
	global_load_dwordx4 v[2:5], v[2:3], off
	v_readlane_b32 s80, v254, 34
	v_readlane_b32 s92, v254, 46
	v_readlane_b32 s93, v254, 47
	v_lshlrev_b32_e32 v120, 2, v24
	v_readlane_b32 s94, v254, 48
	v_readlane_b32 s95, v254, 49
	s_mov_b64 s[68:69], s[92:93]
	s_mov_b64 s[70:71], s[94:95]
	s_waitcnt vmcnt(11)
	v_lshlrev_b32_e32 v86, 16, v66
	v_and_b32_e32 v87, 0xffff0000, v66
	v_lshlrev_b32_e32 v66, 16, v67
	v_and_b32_e32 v67, 0xffff0000, v67
	v_lshlrev_b32_e32 v94, 16, v71
	v_and_b32_e32 v95, 0xffff0000, v71
	v_lshlrev_b32_e32 v92, 16, v70
	v_and_b32_e32 v93, 0xffff0000, v70
	v_lshlrev_b32_e32 v100, 16, v79
	v_and_b32_e32 v101, 0xffff0000, v79
	v_lshlrev_b32_e32 v98, 16, v78
	v_and_b32_e32 v99, 0xffff0000, v78
	v_lshlrev_b32_e32 v108, 16, v73
	v_and_b32_e32 v109, 0xffff0000, v73
	v_lshlrev_b32_e32 v102, 16, v80
	v_and_b32_e32 v103, 0xffff0000, v80
	v_lshlrev_b32_e32 v106, 16, v81
	v_and_b32_e32 v107, 0xffff0000, v81
	v_lshl_or_b32 v136, s63, 7, v149
	v_readlane_b32 s81, v254, 35
	v_readlane_b32 s82, v254, 36
	v_readlane_b32 s83, v254, 37
	v_readlane_b32 s84, v254, 38
	v_readlane_b32 s85, v254, 39
	v_readlane_b32 s86, v254, 40
	v_readlane_b32 s87, v254, 41
	v_readlane_b32 s88, v254, 42
	v_readlane_b32 s89, v254, 43
	v_readlane_b32 s90, v254, 44
	v_readlane_b32 s91, v254, 45
	s_waitcnt vmcnt(10)
	v_lshlrev_b32_e32 v104, 16, v75
	v_and_b32_e32 v105, 0xffff0000, v75
	v_lshlrev_b32_e32 v132, 16, v77
	global_load_dword v164, v[26:27], off
	global_load_dword v165, v[28:29], off offset:128
	global_load_dword v166, v[26:27], off offset:128
	global_load_dword v167, v[28:29], off offset:256
	global_load_dword v168, v[26:27], off offset:256
	global_load_dword v169, v[28:29], off offset:384
	global_load_dword v170, v[26:27], off offset:384
	global_load_dword v171, v[28:29], off offset:512
	global_load_dword v172, v[26:27], off offset:512
	global_load_dword v173, v[28:29], off offset:640
	global_load_dword v174, v[26:27], off offset:640
	global_load_dword v175, v[28:29], off offset:768
	global_load_dword v176, v[26:27], off offset:768
	global_load_dword v177, v[28:29], off offset:896
	global_load_dword v178, v[26:27], off offset:896
	v_or_b32_e32 v190, s65, v152
	v_lshlrev_b32_e32 v190, 13, v190
	v_mov_b32_e32 v191, 0
	v_lshlrev_b32_e32 v192, 1, v136
	v_mov_b32_e32 v193, 0
	v_lshl_add_u64 v[192:193], s[46:47], 0, v[192:193]
	v_lshl_add_u64 v[192:193], v[192:193], 0, v[190:191]
	global_load_dwordx4 v[196:199], v[192:193], off
	v_mov_b32_e32 v190, v192
	v_mov_b32_e32 v191, v193
	v_add_co_u32_e32 v192, vcc, 0x2000, v192
	s_nop 1
	v_addc_co_u32_e32 v193, vcc, 0, v193, vcc
	global_load_dwordx4 v[200:203], v[192:193], off
	v_add_co_u32_e32 v192, vcc, 0x2000, v192
	s_nop 1
	v_addc_co_u32_e32 v193, vcc, 0, v193, vcc
	global_load_dwordx4 v[204:207], v[192:193], off
	v_add_co_u32_e32 v192, vcc, 0x2000, v192
	s_nop 1
	v_addc_co_u32_e32 v193, vcc, 0, v193, vcc
	global_load_dwordx4 v[208:211], v[192:193], off
	v_add_co_u32_e32 v192, vcc, 0x2000, v192
	s_nop 1
	v_addc_co_u32_e32 v193, vcc, 0, v193, vcc
	global_load_dwordx4 v[212:215], v[192:193], off
	v_add_co_u32_e32 v192, vcc, 0x2000, v192
	s_nop 1
	v_addc_co_u32_e32 v193, vcc, 0, v193, vcc
	global_load_dwordx4 v[216:219], v[192:193], off
	v_add_co_u32_e32 v192, vcc, 0x2000, v192
	s_nop 1
	v_addc_co_u32_e32 v193, vcc, 0, v193, vcc
	global_load_dwordx4 v[220:223], v[192:193], off
	v_add_co_u32_e32 v192, vcc, 0x2000, v192
	s_nop 1
	v_addc_co_u32_e32 v193, vcc, 0, v193, vcc
	global_load_dwordx4 v[224:227], v[192:193], off
	s_waitcnt vmcnt(30)
	v_cndmask_b32_e64 v19, 0, v20, s[6:7]
	v_pk_add_f32 v[20:21], v[18:19], v[20:21]
	v_and_b32_e32 v133, 0xffff0000, v77
	v_sub_f32_e32 v180, v20, v21
	v_add_co_u32_e32 v194, vcc, 0xffffa000, v190
	s_nop 1
	v_addc_co_u32_e32 v195, vcc, -1, v191, vcc
	v_lshlrev_b32_e32 v240, 1, v136
	v_mov_b32_e32 v241, 0
	v_lshl_add_u64 v[240:241], s[44:45], 0, v[240:241]
	v_cndmask_b32_e64 v194, v240, v194, s[8:9]
	v_cndmask_b32_e64 v195, v241, v195, s[8:9]
	s_orn2_b64 vcc, s[8:9], s[12:13]
	s_and_saveexec_b64 s[100:101], vcc
	global_load_dwordx4 v[228:231], v[194:195], off
	v_add_co_u32_e32 v194, vcc, 0x2000, v194
	s_nop 1
	v_addc_co_u32_e32 v195, vcc, 0, v195, vcc
	global_load_dwordx4 v[232:235], v[194:195], off
	v_add_co_u32_e32 v194, vcc, 0x2000, v194
	s_nop 1
	v_addc_co_u32_e32 v195, vcc, 0, v195, vcc
	global_load_dwordx4 v[236:239], v[194:195], off
	s_mov_b64 exec, s[100:101]
	s_waitcnt vmcnt(0)
	v_add_f32_e32 v181, v19, v165
	v_sub_f32_e32 v181, v20, v181
	v_add_f32_e32 v182, v19, v167
	v_sub_f32_e32 v182, v20, v182
	v_add_f32_e32 v183, v19, v169
	v_sub_f32_e32 v183, v20, v183
	v_add_f32_e32 v184, v19, v171
	v_sub_f32_e32 v184, v20, v184
	v_add_f32_e32 v185, v19, v173
	v_sub_f32_e32 v185, v20, v185
	v_add_f32_e32 v186, v19, v175
	v_sub_f32_e32 v186, v20, v186
	v_add_f32_e32 v187, v19, v177
	v_sub_f32_e32 v187, v20, v187
	v_exp_f32_e32 v180, v180
	v_exp_f32_e32 v181, v181
	v_exp_f32_e32 v182, v182
	v_exp_f32_e32 v183, v183
	v_exp_f32_e32 v184, v184
	v_exp_f32_e32 v185, v185
	v_exp_f32_e32 v186, v186
	v_exp_f32_e32 v187, v187
	v_mul_f32_e32 v137, v164, v180
	v_mul_f32_e32 v138, v166, v181
	v_mul_f32_e32 v139, v168, v182
	v_mul_f32_e32 v140, v170, v183
	v_mul_f32_e32 v141, v172, v184
	v_mul_f32_e32 v142, v174, v185
	v_mul_f32_e32 v143, v176, v186
	v_mov_b32_e32 v20, v187
	v_mov_b32_e32 v18, v178
	v_lshl_add_u64 v[22:23], s[68:69], 0, v[120:121]
	s_nop 0
	v_lshl_add_u64 v[24:25], v[22:23], 0, s[22:23]
	s_nop 0
	v_lshlrev_b32_e32 v88, 16, v83
	s_nop 0
	v_and_b32_e32 v89, 0xffff0000, v83
	s_nop 0
	v_lshlrev_b32_e32 v90, 16, v84
	s_nop 0
	v_add_co_u32_e32 v26, vcc, s58, v22
	s_nop 0
	v_addc_co_u32_e32 v27, vcc, 0, v23, vcc
	v_add_co_u32_e32 v30, vcc, s59, v22
	v_and_b32_e32 v91, 0xffff0000, v84
	s_nop 0
	v_addc_co_u32_e32 v31, vcc, 0, v23, vcc
	v_lshlrev_b32_e32 v96, 16, v85
	v_and_b32_e32 v97, 0xffff0000, v85
	v_lshlrev_b32_e32 v130, 16, v61
	v_and_b32_e32 v131, 0xffff0000, v61
	s_waitcnt vmcnt(5)
	v_mul_f32_e32 v144, v18, v20
	global_load_dwordx4 v[18:21], v120, s[68:69] offset:16
	global_load_dwordx4 v[42:45], v120, s[68:69]
	global_load_dwordx4 v[50:53], v[26:27], off
	s_nop 0
	global_load_dwordx4 v[26:29], v[24:25], off offset:16
	v_lshl_add_u64 v[24:25], v[22:23], 0, s[26:27]
	global_load_dwordx4 v[54:57], v[30:31], off
	s_nop 0
	global_load_dwordx4 v[30:33], v[24:25], off offset:16
	v_lshl_add_u64 v[24:25], v[22:23], 0, s[30:31]
	v_add_co_u32_e32 v22, vcc, s60, v22
	s_waitcnt vmcnt(10)
	v_lshlrev_b32_e32 v114, 16, v39
	v_addc_co_u32_e32 v23, vcc, 0, v23, vcc
	global_load_dwordx4 v[46:49], v[22:23], off
	s_nop 0
	global_load_dwordx4 v[22:25], v[24:25], off offset:16
	s_nop 0
	global_load_dwordx4 v[34:37], v120, s[70:71] offset:16
	global_load_dwordx4 v[62:65], v120, s[70:71]
	v_and_b32_e32 v115, 0xffff0000, v39
	v_lshlrev_b32_e32 v110, 16, v38
	v_and_b32_e32 v111, 0xffff0000, v38
	v_lshlrev_b32_e32 v116, 16, v41
	v_and_b32_e32 v117, 0xffff0000, v41
	s_waitcnt vmcnt(13)
	v_lshlrev_b32_e32 v112, 16, v15
	v_and_b32_e32 v113, 0xffff0000, v15
	s_waitcnt vmcnt(12)
	v_lshlrev_b32_e32 v134, 16, v11
	v_and_b32_e32 v135, 0xffff0000, v11
	v_lshlrev_b32_e32 v120, 1, v136
	s_waitcnt vmcnt(0)
	v_pk_fma_f32 v[66:67], v[44:45], v[66:67], v[64:65]
	v_pk_fma_f32 v[86:87], v[42:43], v[86:87], v[62:63]
	v_pk_fma_f32 v[66:67], v[52:53], v[94:95], v[66:67]
	v_pk_fma_f32 v[70:71], v[50:51], v[92:93], v[86:87]
	v_pk_fma_f32 v[66:67], v[56:57], v[100:101], v[66:67]
	v_pk_fma_f32 v[70:71], v[54:55], v[98:99], v[70:71]
	v_lshlrev_b32_e32 v86, 16, v82
	v_and_b32_e32 v87, 0xffff0000, v82
	v_pk_fma_f32 v[66:67], v[48:49], v[88:89], v[66:67]
	v_pk_fma_f32 v[70:71], v[46:47], v[86:87], v[70:71]
	v_pk_mul_f32 v[78:79], v[66:67], s[36:37] op_sel_hi:[1,0]
	v_pk_mul_f32 v[82:83], v[70:71], s[36:37] op_sel_hi:[1,0]
	v_exp_f32_e32 v78, v78
	v_exp_f32_e32 v79, v79
	v_exp_f32_e32 v82, v82
	v_exp_f32_e32 v83, v83
	v_pk_add_f32 v[78:79], v[78:79], 1.0 op_sel_hi:[1,0]
	s_nop 0
	v_rcp_f32_e32 v78, v78
	v_pk_add_f32 v[82:83], v[82:83], 1.0 op_sel_hi:[1,0]
	v_rcp_f32_e32 v79, v79
	v_rcp_f32_e32 v82, v82
	v_rcp_f32_e32 v83, v83
	v_pk_mul_f32 v[66:67], v[66:67], v[78:79]
	v_lshlrev_b32_e32 v78, 16, v68
	v_and_b32_e32 v79, 0xffff0000, v68
	v_lshlrev_b32_e32 v68, 16, v69
	v_and_b32_e32 v69, 0xffff0000, v69
	v_pk_mul_f32 v[70:71], v[70:71], v[82:83]
	v_pk_fma_f32 v[68:69], v[20:21], v[68:69], v[36:37]
	v_pk_fma_f32 v[78:79], v[18:19], v[78:79], v[34:35]
	v_lshlrev_b32_e32 v82, 16, v72
	v_and_b32_e32 v83, 0xffff0000, v72
	v_pk_fma_f32 v[68:69], v[28:29], v[108:109], v[68:69]
	v_pk_fma_f32 v[72:73], v[26:27], v[82:83], v[78:79]
	v_pk_fma_f32 v[68:69], v[32:33], v[106:107], v[68:69]
	v_pk_fma_f32 v[72:73], v[30:31], v[102:103], v[72:73]
	v_pk_fma_f32 v[68:69], v[24:25], v[96:97], v[68:69]
	v_pk_fma_f32 v[72:73], v[22:23], v[90:91], v[72:73]
	v_pk_mul_f32 v[78:79], v[68:69], s[36:37] op_sel_hi:[1,0]
	v_pk_mul_f32 v[80:81], v[72:73], s[36:37] op_sel_hi:[1,0]
	v_exp_f32_e32 v78, v78
	v_exp_f32_e32 v80, v80
	v_exp_f32_e32 v81, v81
	v_exp_f32_e32 v79, v79
	v_pk_fma_f32 v[82:83], v[18:19], v[82:83], v[34:35]
	v_pk_add_f32 v[80:81], v[80:81], 1.0 op_sel_hi:[1,0]
	v_pk_add_f32 v[78:79], v[78:79], 1.0 op_sel_hi:[1,0]
	v_rcp_f32_e32 v80, v80
	v_rcp_f32_e32 v81, v81
	v_rcp_f32_e32 v78, v78
	v_rcp_f32_e32 v79, v79
	v_pk_fma_f32 v[82:83], v[26:27], v[102:103], v[82:83]
	v_pk_mul_f32 v[72:73], v[72:73], v[80:81]
	v_pk_fma_f32 v[80:81], v[42:43], v[92:93], v[62:63]
	v_pk_mul_f32 v[68:69], v[68:69], v[78:79]
	v_pk_fma_f32 v[78:79], v[44:45], v[94:95], v[64:65]
	v_pk_fma_f32 v[80:81], v[50:51], v[98:99], v[80:81]
	v_pk_fma_f32 v[78:79], v[52:53], v[100:101], v[78:79]
	v_pk_fma_f32 v[80:81], v[54:55], v[86:87], v[80:81]
	v_pk_fma_f32 v[78:79], v[56:57], v[88:89], v[78:79]
	v_lshlrev_b32_e32 v92, 16, v74
	v_and_b32_e32 v93, 0xffff0000, v74
	v_pk_fma_f32 v[80:81], v[46:47], v[92:93], v[80:81]
	v_pk_fma_f32 v[74:75], v[48:49], v[104:105], v[78:79]
	v_pk_mul_f32 v[84:85], v[80:81], s[36:37] op_sel_hi:[1,0]
	v_pk_mul_f32 v[78:79], v[74:75], s[36:37] op_sel_hi:[1,0]
	v_exp_f32_e32 v84, v84
	v_exp_f32_e32 v85, v85
	v_exp_f32_e32 v78, v78
	v_exp_f32_e32 v79, v79
	v_pk_fma_f32 v[82:83], v[30:31], v[90:91], v[82:83]
	v_pk_add_f32 v[84:85], v[84:85], 1.0 op_sel_hi:[1,0]
	v_lshlrev_b32_e32 v94, 16, v76
	v_pk_add_f32 v[78:79], v[78:79], 1.0 op_sel_hi:[1,0]
	v_rcp_f32_e32 v84, v84
	v_rcp_f32_e32 v85, v85
	v_rcp_f32_e32 v78, v78
	v_rcp_f32_e32 v79, v79
	v_and_b32_e32 v95, 0xffff0000, v76
	v_pk_fma_f32 v[82:83], v[22:23], v[94:95], v[82:83]
	v_pk_fma_f32 v[102:103], v[18:19], v[102:103], v[34:35]
	v_pk_mul_f32 v[74:75], v[74:75], v[78:79]
	v_pk_mul_f32 v[78:79], v[80:81], v[84:85]
	v_pk_fma_f32 v[80:81], v[20:21], v[108:109], v[36:37]
	v_pk_mul_f32 v[84:85], v[82:83], s[36:37] op_sel_hi:[1,0]
	v_pk_fma_f32 v[80:81], v[28:29], v[106:107], v[80:81]
	v_exp_f32_e32 v84, v84
	v_pk_fma_f32 v[80:81], v[32:33], v[96:97], v[80:81]
	v_exp_f32_e32 v85, v85
	v_pk_fma_f32 v[76:77], v[24:25], v[132:133], v[80:81]
	v_pk_fma_f32 v[102:103], v[26:27], v[90:91], v[102:103]
	v_pk_mul_f32 v[80:81], v[76:77], s[36:37] op_sel_hi:[1,0]
	v_pk_add_f32 v[84:85], v[84:85], 1.0 op_sel_hi:[1,0]
	v_exp_f32_e32 v80, v80
	v_exp_f32_e32 v81, v81
	v_rcp_f32_e32 v84, v84
	v_rcp_f32_e32 v85, v85
	v_pk_fma_f32 v[90:91], v[18:19], v[90:91], v[34:35]
	v_pk_add_f32 v[80:81], v[80:81], 1.0 op_sel_hi:[1,0]
	v_pk_fma_f32 v[90:91], v[26:27], v[94:95], v[90:91]
	v_rcp_f32_e32 v80, v80
	v_rcp_f32_e32 v81, v81
	s_nop 0
	v_pk_mul_f32 v[76:77], v[76:77], v[80:81]
	v_pk_mul_f32 v[80:81], v[82:83], v[84:85]
	v_pk_fma_f32 v[82:83], v[44:45], v[100:101], v[64:65]
	v_pk_fma_f32 v[84:85], v[42:43], v[98:99], v[62:63]
	v_pk_fma_f32 v[82:83], v[52:53], v[88:89], v[82:83]
	v_pk_fma_f32 v[84:85], v[50:51], v[86:87], v[84:85]
	v_pk_fma_f32 v[82:83], v[56:57], v[104:105], v[82:83]
	v_pk_fma_f32 v[84:85], v[54:55], v[92:93], v[84:85]
	v_lshlrev_b32_e32 v98, 16, v58
	v_and_b32_e32 v99, 0xffff0000, v58
	v_lshlrev_b32_e32 v100, 16, v59
	v_and_b32_e32 v101, 0xffff0000, v59
	v_pk_fma_f32 v[84:85], v[46:47], v[98:99], v[84:85]
	v_pk_fma_f32 v[58:59], v[48:49], v[100:101], v[82:83]
	v_pk_mul_f32 v[108:109], v[84:85], s[36:37] op_sel_hi:[1,0]
	v_pk_mul_f32 v[82:83], v[58:59], s[36:37] op_sel_hi:[1,0]
	v_exp_f32_e32 v108, v108
	v_exp_f32_e32 v109, v109
	v_exp_f32_e32 v82, v82
	v_exp_f32_e32 v83, v83
	v_pk_fma_f32 v[88:89], v[44:45], v[88:89], v[64:65]
	v_pk_add_f32 v[108:109], v[108:109], 1.0 op_sel_hi:[1,0]
	v_pk_fma_f32 v[88:89], v[52:53], v[104:105], v[88:89]
	v_pk_add_f32 v[82:83], v[82:83], 1.0 op_sel_hi:[1,0]
	v_rcp_f32_e32 v108, v108
	v_rcp_f32_e32 v109, v109
	v_rcp_f32_e32 v82, v82
	v_rcp_f32_e32 v83, v83
	v_pk_fma_f32 v[86:87], v[42:43], v[86:87], v[62:63]
	v_pk_fma_f32 v[88:89], v[56:57], v[100:101], v[88:89]
	v_pk_fma_f32 v[86:87], v[50:51], v[92:93], v[86:87]
	v_pk_mul_f32 v[58:59], v[58:59], v[82:83]
	v_pk_mul_f32 v[82:83], v[84:85], v[108:109]
	v_pk_fma_f32 v[84:85], v[20:21], v[106:107], v[36:37]
	v_pk_fma_f32 v[106:107], v[30:31], v[94:95], v[102:103]
	v_pk_fma_f32 v[84:85], v[28:29], v[96:97], v[84:85]
	v_lshlrev_b32_e32 v102, 16, v60
	v_pk_fma_f32 v[84:85], v[32:33], v[132:133], v[84:85]
	v_and_b32_e32 v103, 0xffff0000, v60
	v_pk_fma_f32 v[106:107], v[22:23], v[102:103], v[106:107]
	v_pk_fma_f32 v[60:61], v[24:25], v[130:131], v[84:85]
	v_pk_mul_f32 v[108:109], v[106:107], s[36:37] op_sel_hi:[1,0]
	v_pk_mul_f32 v[84:85], v[60:61], s[36:37] op_sel_hi:[1,0]
	v_exp_f32_e32 v108, v108
	v_exp_f32_e32 v109, v109
	v_exp_f32_e32 v84, v84
	v_exp_f32_e32 v85, v85
	v_pk_fma_f32 v[38:39], v[48:49], v[114:115], v[88:89]
	v_pk_add_f32 v[108:109], v[108:109], 1.0 op_sel_hi:[1,0]
	v_pk_fma_f32 v[86:87], v[54:55], v[98:99], v[86:87]
	v_pk_add_f32 v[84:85], v[84:85], 1.0 op_sel_hi:[1,0]
	v_rcp_f32_e32 v108, v108
	v_rcp_f32_e32 v109, v109
	v_rcp_f32_e32 v84, v84
	v_rcp_f32_e32 v85, v85
	v_pk_mul_f32 v[88:89], v[38:39], s[36:37] op_sel_hi:[1,0]
	v_pk_fma_f32 v[86:87], v[46:47], v[110:111], v[86:87]
	v_exp_f32_e32 v88, v88
	v_exp_f32_e32 v89, v89
	v_pk_mul_f32 v[60:61], v[60:61], v[84:85]
	v_pk_mul_f32 v[84:85], v[106:107], v[108:109]
	v_pk_mul_f32 v[106:107], v[86:87], s[36:37] op_sel_hi:[1,0]
	v_pk_add_f32 v[88:89], v[88:89], 1.0 op_sel_hi:[1,0]
	v_exp_f32_e32 v106, v106
	v_exp_f32_e32 v107, v107
	v_rcp_f32_e32 v88, v88
	v_rcp_f32_e32 v89, v89
	v_pk_fma_f32 v[90:91], v[30:31], v[102:103], v[90:91]
	v_pk_add_f32 v[106:107], v[106:107], 1.0 op_sel_hi:[1,0]
	v_lshlrev_b32_e32 v108, 16, v14
	v_rcp_f32_e32 v106, v106
	v_rcp_f32_e32 v107, v107
	v_pk_mul_f32 v[38:39], v[38:39], v[88:89]
	v_pk_fma_f32 v[88:89], v[20:21], v[96:97], v[36:37]
	v_and_b32_e32 v109, 0xffff0000, v14
	v_pk_fma_f32 v[88:89], v[28:29], v[132:133], v[88:89]
	v_pk_mul_f32 v[86:87], v[86:87], v[106:107]
	v_pk_fma_f32 v[88:89], v[32:33], v[130:131], v[88:89]
	v_lshlrev_b32_e32 v106, 16, v40
	v_and_b32_e32 v107, 0xffff0000, v40
	v_pk_fma_f32 v[90:91], v[22:23], v[106:107], v[90:91]
	v_pk_fma_f32 v[40:41], v[24:25], v[116:117], v[88:89]
	v_pk_mul_f32 v[96:97], v[90:91], s[36:37] op_sel_hi:[1,0]
	v_pk_mul_f32 v[88:89], v[40:41], s[36:37] op_sel_hi:[1,0]
	v_exp_f32_e32 v96, v96
	v_exp_f32_e32 v97, v97
	v_exp_f32_e32 v88, v88
	v_exp_f32_e32 v89, v89
	v_pk_fma_f32 v[94:95], v[18:19], v[94:95], v[34:35]
	v_pk_add_f32 v[96:97], v[96:97], 1.0 op_sel_hi:[1,0]
	v_pk_fma_f32 v[94:95], v[26:27], v[102:103], v[94:95]
	v_pk_add_f32 v[88:89], v[88:89], 1.0 op_sel_hi:[1,0]
	v_rcp_f32_e32 v96, v96
	v_rcp_f32_e32 v97, v97
	v_rcp_f32_e32 v88, v88
	v_rcp_f32_e32 v89, v89
	v_pk_fma_f32 v[94:95], v[30:31], v[106:107], v[94:95]
	v_pk_fma_f32 v[102:103], v[18:19], v[102:103], v[34:35]
	v_pk_mul_f32 v[40:41], v[40:41], v[88:89]
	v_pk_mul_f32 v[88:89], v[90:91], v[96:97]
	v_pk_fma_f32 v[90:91], v[42:43], v[92:93], v[62:63]
	v_pk_fma_f32 v[92:93], v[44:45], v[104:105], v[64:65]
	v_pk_fma_f32 v[90:91], v[50:51], v[98:99], v[90:91]
	v_pk_fma_f32 v[92:93], v[52:53], v[100:101], v[92:93]
	v_pk_fma_f32 v[90:91], v[54:55], v[110:111], v[90:91]
	v_pk_fma_f32 v[92:93], v[56:57], v[114:115], v[92:93]
	v_pk_fma_f32 v[100:101], v[44:45], v[100:101], v[64:65]
	v_pk_fma_f32 v[14:15], v[48:49], v[112:113], v[92:93]
	v_pk_fma_f32 v[92:93], v[46:47], v[108:109], v[90:91]
	v_pk_mul_f32 v[90:91], v[14:15], s[36:37] op_sel_hi:[1,0]
	v_pk_mul_f32 v[96:97], v[92:93], s[36:37] op_sel_hi:[1,0]
	v_exp_f32_e32 v90, v90
	v_exp_f32_e32 v91, v91
	v_exp_f32_e32 v96, v96
	v_exp_f32_e32 v97, v97
	v_pk_fma_f32 v[98:99], v[42:43], v[98:99], v[62:63]
	v_pk_add_f32 v[90:91], v[90:91], 1.0 op_sel_hi:[1,0]
	v_pk_fma_f32 v[100:101], v[52:53], v[114:115], v[100:101]
	v_rcp_f32_e32 v90, v90
	v_rcp_f32_e32 v91, v91
	v_pk_add_f32 v[96:97], v[96:97], 1.0 op_sel_hi:[1,0]
	v_pk_fma_f32 v[98:99], v[50:51], v[110:111], v[98:99]
	v_rcp_f32_e32 v96, v96
	v_rcp_f32_e32 v97, v97
	v_pk_mul_f32 v[90:91], v[14:15], v[90:91]
	v_pk_fma_f32 v[14:15], v[20:21], v[132:133], v[36:37]
	v_pk_fma_f32 v[100:101], v[56:57], v[112:113], v[100:101]
	v_pk_fma_f32 v[14:15], v[28:29], v[130:131], v[14:15]
	v_pk_mul_f32 v[92:93], v[92:93], v[96:97]
	v_pk_fma_f32 v[96:97], v[32:33], v[116:117], v[14:15]
	v_lshlrev_b32_e32 v14, 16, v16
	v_and_b32_e32 v15, 0xffff0000, v16
	v_lshlrev_b32_e32 v16, 16, v17
	v_and_b32_e32 v17, 0xffff0000, v17
	v_pk_fma_f32 v[104:105], v[22:23], v[14:15], v[94:95]
	v_pk_fma_f32 v[94:95], v[24:25], v[16:17], v[96:97]
	v_pk_mul_f32 v[132:133], v[104:105], s[36:37] op_sel_hi:[1,0]
	v_pk_mul_f32 v[96:97], v[94:95], s[36:37] op_sel_hi:[1,0]
	v_exp_f32_e32 v132, v132
	v_exp_f32_e32 v133, v133
	v_exp_f32_e32 v96, v96
	v_exp_f32_e32 v97, v97
	v_pk_fma_f32 v[98:99], v[54:55], v[108:109], v[98:99]
	v_pk_add_f32 v[132:133], v[132:133], 1.0 op_sel_hi:[1,0]
	v_pk_fma_f32 v[102:103], v[26:27], v[106:107], v[102:103]
	v_pk_add_f32 v[96:97], v[96:97], 1.0 op_sel_hi:[1,0]
	v_rcp_f32_e32 v132, v132
	v_rcp_f32_e32 v133, v133
	v_rcp_f32_e32 v96, v96
	v_rcp_f32_e32 v97, v97
	v_pk_fma_f32 v[102:103], v[30:31], v[14:15], v[102:103]
	v_pk_fma_f32 v[114:115], v[44:45], v[114:115], v[64:65]
	v_pk_fma_f32 v[110:111], v[42:43], v[110:111], v[62:63]
	v_pk_mul_f32 v[94:95], v[94:95], v[96:97]
	v_pk_mul_f32 v[96:97], v[104:105], v[132:133]
	v_lshlrev_b32_e32 v132, 16, v10
	v_and_b32_e32 v133, 0xffff0000, v10
	v_pk_fma_f32 v[10:11], v[48:49], v[134:135], v[100:101]
	v_pk_fma_f32 v[100:101], v[46:47], v[132:133], v[98:99]
	v_pk_mul_f32 v[98:99], v[10:11], s[36:37] op_sel_hi:[1,0]
	v_pk_mul_f32 v[104:105], v[100:101], s[36:37] op_sel_hi:[1,0]
	v_exp_f32_e32 v98, v98
	v_exp_f32_e32 v99, v99
	v_exp_f32_e32 v104, v104
	v_exp_f32_e32 v105, v105
	v_pk_fma_f32 v[114:115], v[52:53], v[112:113], v[114:115]
	v_pk_add_f32 v[98:99], v[98:99], 1.0 op_sel_hi:[1,0]
	v_pk_fma_f32 v[42:43], v[42:43], v[108:109], v[62:63]
	v_rcp_f32_e32 v98, v98
	v_rcp_f32_e32 v99, v99
	v_pk_add_f32 v[104:105], v[104:105], 1.0 op_sel_hi:[1,0]
	v_pk_fma_f32 v[44:45], v[44:45], v[112:113], v[64:65]
	v_rcp_f32_e32 v104, v104
	v_rcp_f32_e32 v105, v105
	v_pk_mul_f32 v[98:99], v[10:11], v[98:99]
	v_pk_fma_f32 v[10:11], v[20:21], v[130:131], v[36:37]
	v_pk_fma_f32 v[114:115], v[56:57], v[134:135], v[114:115]
	v_pk_fma_f32 v[10:11], v[28:29], v[116:117], v[10:11]
	v_pk_mul_f32 v[100:101], v[100:101], v[104:105]
	v_pk_fma_f32 v[104:105], v[32:33], v[16:17], v[10:11]
	v_lshlrev_b32_e32 v10, 16, v12
	v_and_b32_e32 v11, 0xffff0000, v12
	v_lshlrev_b32_e32 v12, 16, v13
	v_and_b32_e32 v13, 0xffff0000, v13
	v_pk_fma_f32 v[130:131], v[22:23], v[10:11], v[102:103]
	v_pk_fma_f32 v[102:103], v[24:25], v[12:13], v[104:105]
	v_pk_mul_f32 v[146:147], v[130:131], s[36:37] op_sel_hi:[1,0]
	v_pk_mul_f32 v[104:105], v[102:103], s[36:37] op_sel_hi:[1,0]
	v_exp_f32_e32 v146, v146
	v_exp_f32_e32 v147, v147
	v_exp_f32_e32 v104, v104
	v_exp_f32_e32 v105, v105
	v_pk_fma_f32 v[44:45], v[52:53], v[134:135], v[44:45]
	v_pk_add_f32 v[146:147], v[146:147], 1.0 op_sel_hi:[1,0]
	v_pk_fma_f32 v[42:43], v[50:51], v[132:133], v[42:43]
	v_pk_add_f32 v[104:105], v[104:105], 1.0 op_sel_hi:[1,0]
	v_rcp_f32_e32 v146, v146
	v_rcp_f32_e32 v147, v147
	v_rcp_f32_e32 v104, v104
	v_rcp_f32_e32 v105, v105
	v_pk_fma_f32 v[110:111], v[50:51], v[108:109], v[110:111]
	v_pk_fma_f32 v[116:117], v[20:21], v[116:117], v[36:37]
	v_pk_fma_f32 v[110:111], v[54:55], v[132:133], v[110:111]
	v_pk_mul_f32 v[102:103], v[102:103], v[104:105]
	v_pk_mul_f32 v[104:105], v[130:131], v[146:147]
	v_lshlrev_b32_e32 v130, 16, v6
	v_and_b32_e32 v131, 0xffff0000, v6
	v_lshlrev_b32_e32 v6, 16, v7
	v_and_b32_e32 v7, 0xffff0000, v7
	v_pk_fma_f32 v[114:115], v[48:49], v[6:7], v[114:115]
	v_pk_fma_f32 v[6:7], v[56:57], v[6:7], v[44:45]
	v_pk_fma_f32 v[42:43], v[54:55], v[130:131], v[42:43]
	v_lshlrev_b32_e32 v44, 16, v2
	v_and_b32_e32 v45, 0xffff0000, v2
	v_lshlrev_b32_e32 v2, 16, v3
	v_and_b32_e32 v3, 0xffff0000, v3
	v_pk_fma_f32 v[2:3], v[48:49], v[2:3], v[6:7]
	v_pk_fma_f32 v[6:7], v[46:47], v[44:45], v[42:43]
	v_pk_fma_f32 v[146:147], v[46:47], v[130:131], v[110:111]
	v_pk_mul_f32 v[42:43], v[2:3], s[36:37] op_sel_hi:[1,0]
	v_pk_mul_f32 v[44:45], v[6:7], s[36:37] op_sel_hi:[1,0]
	v_pk_mul_f32 v[110:111], v[114:115], s[36:37] op_sel_hi:[1,0]
	v_pk_mul_f32 v[160:161], v[146:147], s[36:37] op_sel_hi:[1,0]
	v_exp_f32_e32 v44, v44
	v_exp_f32_e32 v45, v45
	v_exp_f32_e32 v42, v42
	v_exp_f32_e32 v43, v43
	v_exp_f32_e32 v160, v160
	v_exp_f32_e32 v161, v161
	v_exp_f32_e32 v110, v110
	v_exp_f32_e32 v111, v111
	v_pk_add_f32 v[42:43], v[42:43], 1.0 op_sel_hi:[1,0]
	v_pk_add_f32 v[44:45], v[44:45], 1.0 op_sel_hi:[1,0]
	v_pk_add_f32 v[160:161], v[160:161], 1.0 op_sel_hi:[1,0]
	v_pk_add_f32 v[110:111], v[110:111], 1.0 op_sel_hi:[1,0]
	v_rcp_f32_e32 v44, v44
	v_rcp_f32_e32 v45, v45
	v_rcp_f32_e32 v42, v42
	v_rcp_f32_e32 v43, v43
	v_rcp_f32_e32 v160, v160
	v_rcp_f32_e32 v161, v161
	v_rcp_f32_e32 v110, v110
	v_rcp_f32_e32 v111, v111
	v_pk_fma_f32 v[106:107], v[18:19], v[106:107], v[34:35]
	v_pk_fma_f32 v[116:117], v[28:29], v[16:17], v[116:117]
	v_pk_fma_f32 v[106:107], v[26:27], v[14:15], v[106:107]
	v_pk_mul_f32 v[42:43], v[2:3], v[42:43]
	v_pk_mul_f32 v[44:45], v[6:7], v[44:45]
	v_pk_fma_f32 v[2:3], v[20:21], v[16:17], v[36:37]
	v_pk_fma_f32 v[6:7], v[18:19], v[14:15], v[34:35]
	v_pk_mul_f32 v[110:111], v[114:115], v[110:111]
	v_pk_mul_f32 v[114:115], v[146:147], v[160:161]
	v_pk_fma_f32 v[116:117], v[32:33], v[12:13], v[116:117]
	v_pk_fma_f32 v[106:107], v[30:31], v[10:11], v[106:107]
	v_lshlrev_b32_e32 v146, 16, v8
	v_and_b32_e32 v147, 0xffff0000, v8
	v_lshlrev_b32_e32 v8, 16, v9
	v_and_b32_e32 v9, 0xffff0000, v9
	v_pk_fma_f32 v[6:7], v[26:27], v[10:11], v[6:7]
	v_pk_fma_f32 v[2:3], v[28:29], v[12:13], v[2:3]
	v_pk_fma_f32 v[160:161], v[22:23], v[146:147], v[106:107]
	v_pk_fma_f32 v[106:107], v[24:25], v[8:9], v[116:117]
	v_pk_fma_f32 v[2:3], v[32:33], v[8:9], v[2:3]
	v_pk_fma_f32 v[6:7], v[30:31], v[146:147], v[6:7]
	v_lshlrev_b32_e32 v8, 16, v4
	v_and_b32_e32 v9, 0xffff0000, v4
	v_lshlrev_b32_e32 v4, 16, v5
	v_and_b32_e32 v5, 0xffff0000, v5
	v_pk_fma_f32 v[6:7], v[22:23], v[8:9], v[6:7]
	v_pk_fma_f32 v[2:3], v[24:25], v[4:5], v[2:3]
	v_pk_mul_f32 v[8:9], v[6:7], s[36:37] op_sel_hi:[1,0]
	v_pk_mul_f32 v[4:5], v[2:3], s[36:37] op_sel_hi:[1,0]
	v_exp_f32_e32 v8, v8
	v_exp_f32_e32 v9, v9
	v_exp_f32_e32 v4, v4
	v_exp_f32_e32 v5, v5
	v_mul_f32_e32 v10, v137, v69
	v_pk_add_f32 v[8:9], v[8:9], 1.0 op_sel_hi:[1,0]
	v_mul_f32_e32 v11, v138, v79
	v_pk_add_f32 v[4:5], v[4:5], 1.0 op_sel_hi:[1,0]
	v_rcp_f32_e32 v8, v8
	v_rcp_f32_e32 v9, v9
	v_rcp_f32_e32 v4, v4
	v_rcp_f32_e32 v5, v5
	v_mul_f32_e32 v12, v138, v75
	v_pk_mul_f32 v[36:37], v[6:7], v[8:9]
	v_mul_f32_e32 v6, v137, v70
	v_mul_f32_e32 v7, v137, v71
	v_pk_mul_f32 v[46:47], v[2:3], v[4:5]
	v_cvt_pk_bf16_f32 v2, v70, v71
	v_cvt_pk_bf16_f32 v3, v66, v67
	v_cvt_pk_bf16_f32 v4, v72, v73
	v_cvt_pk_bf16_f32 v5, v68, v69
	v_cvt_pk_bf16_f32 v6, v6, v7
	v_mul_f32_e32 v7, v137, v66
	v_mul_f32_e32 v8, v137, v67
	v_cvt_pk_bf16_f32 v7, v7, v8
	v_mul_f32_e32 v8, v137, v72
	v_mul_f32_e32 v9, v137, v73
	v_cvt_pk_bf16_f32 v8, v8, v9
	v_mul_f32_e32 v9, v137, v68
	v_cvt_pk_bf16_f32 v9, v9, v10
	v_mul_f32_e32 v10, v138, v78
	ds_write_b128 v156, v[6:9]
	v_cvt_pk_bf16_f32 v6, v78, v79
	v_cvt_pk_bf16_f32 v7, v74, v75
	v_cvt_pk_bf16_f32 v8, v80, v81
	v_cvt_pk_bf16_f32 v9, v76, v77
	v_cvt_pk_bf16_f32 v10, v10, v11
	v_mul_f32_e32 v11, v138, v74
	v_cvt_pk_bf16_f32 v11, v11, v12
	v_mul_f32_e32 v12, v138, v80
	v_mul_f32_e32 v13, v138, v81
	v_cvt_pk_bf16_f32 v12, v12, v13
	v_mul_f32_e32 v13, v138, v76
	v_mul_f32_e32 v14, v138, v77
	v_cvt_pk_bf16_f32 v13, v13, v14
	v_mul_f32_e32 v14, v139, v82
	v_mul_f32_e32 v15, v139, v83
	ds_write_b128 v156, v[10:13] offset:64
	v_cvt_pk_bf16_f32 v10, v82, v83
	v_cvt_pk_bf16_f32 v11, v58, v59
	v_cvt_pk_bf16_f32 v12, v84, v85
	v_cvt_pk_bf16_f32 v13, v60, v61
	v_cvt_pk_bf16_f32 v14, v14, v15
	v_mul_f32_e32 v15, v139, v58
	v_mul_f32_e32 v16, v139, v59
	v_cvt_pk_bf16_f32 v15, v15, v16
	v_mul_f32_e32 v16, v139, v84
	v_mul_f32_e32 v17, v139, v85
	v_cvt_pk_bf16_f32 v16, v16, v17
	v_mul_f32_e32 v17, v139, v60
	v_mul_f32_e32 v18, v139, v61
	v_cvt_pk_bf16_f32 v17, v17, v18
	v_mul_f32_e32 v18, v140, v86
	v_mul_f32_e32 v19, v140, v87
	ds_write_b128 v156, v[14:17] offset:128
	v_cvt_pk_bf16_f32 v14, v86, v87
	v_cvt_pk_bf16_f32 v15, v38, v39
	v_cvt_pk_bf16_f32 v16, v88, v89
	v_cvt_pk_bf16_f32 v17, v40, v41
	v_cvt_pk_bf16_f32 v18, v18, v19
	v_mul_f32_e32 v19, v140, v38
	v_mul_f32_e32 v20, v140, v39
	v_cvt_pk_bf16_f32 v19, v19, v20
	v_mul_f32_e32 v20, v140, v88
	v_mul_f32_e32 v21, v140, v89
	v_pk_mul_f32 v[116:117], v[106:107], s[36:37] op_sel_hi:[1,0]
	v_pk_mul_f32 v[162:163], v[160:161], s[36:37] op_sel_hi:[1,0]
	v_cvt_pk_bf16_f32 v20, v20, v21
	v_mul_f32_e32 v21, v140, v40
	v_mul_f32_e32 v22, v140, v41
	v_exp_f32_e32 v162, v162
	v_exp_f32_e32 v163, v163
	v_exp_f32_e32 v116, v116
	v_exp_f32_e32 v117, v117
	v_cvt_pk_bf16_f32 v21, v21, v22
	v_mul_f32_e32 v22, v141, v92
	v_mul_f32_e32 v23, v141, v93
	ds_write_b128 v156, v[18:21] offset:192
	v_cvt_pk_bf16_f32 v18, v92, v93
	v_cvt_pk_bf16_f32 v19, v90, v91
	v_cvt_pk_bf16_f32 v20, v96, v97
	v_cvt_pk_bf16_f32 v21, v94, v95
	v_cvt_pk_bf16_f32 v22, v22, v23
	v_mul_f32_e32 v23, v141, v90
	v_mul_f32_e32 v24, v141, v91
	v_cvt_pk_bf16_f32 v23, v23, v24
	v_mul_f32_e32 v24, v141, v96
	v_mul_f32_e32 v25, v141, v97
	v_cvt_pk_bf16_f32 v24, v24, v25
	v_mul_f32_e32 v25, v141, v94
	v_mul_f32_e32 v26, v141, v95
	v_pk_add_f32 v[116:117], v[116:117], 1.0 op_sel_hi:[1,0]
	v_pk_add_f32 v[162:163], v[162:163], 1.0 op_sel_hi:[1,0]
	v_cvt_pk_bf16_f32 v25, v25, v26
	v_mul_f32_e32 v26, v142, v100
	v_mul_f32_e32 v27, v142, v101
	v_rcp_f32_e32 v162, v162
	v_rcp_f32_e32 v163, v163
	v_rcp_f32_e32 v116, v116
	v_rcp_f32_e32 v117, v117
	ds_write_b128 v156, v[22:25] offset:256
	v_cvt_pk_bf16_f32 v22, v100, v101
	v_cvt_pk_bf16_f32 v23, v98, v99
	v_cvt_pk_bf16_f32 v24, v104, v105
	v_cvt_pk_bf16_f32 v25, v102, v103
	v_cvt_pk_bf16_f32 v26, v26, v27
	v_mul_f32_e32 v27, v142, v98
	v_mul_f32_e32 v28, v142, v99
	v_cvt_pk_bf16_f32 v27, v27, v28
	v_mul_f32_e32 v28, v142, v104
	v_mul_f32_e32 v29, v142, v105
	v_cvt_pk_bf16_f32 v28, v28, v29
	v_mul_f32_e32 v29, v142, v102
	v_mul_f32_e32 v30, v142, v103
	v_cvt_pk_bf16_f32 v29, v29, v30
	v_mul_f32_e32 v30, v143, v114
	v_mul_f32_e32 v31, v143, v115
	v_pk_mul_f32 v[106:107], v[106:107], v[116:117]
	v_pk_mul_f32 v[116:117], v[160:161], v[162:163]
	ds_write_b128 v156, v[26:29] offset:320
	v_cvt_pk_bf16_f32 v26, v114, v115
	v_cvt_pk_bf16_f32 v27, v110, v111
	v_cvt_pk_bf16_f32 v28, v116, v117
	v_cvt_pk_bf16_f32 v29, v106, v107
	v_cvt_pk_bf16_f32 v30, v30, v31
	v_mul_f32_e32 v31, v143, v110
	v_mul_f32_e32 v32, v143, v111
	v_cvt_pk_bf16_f32 v31, v31, v32
	v_mul_f32_e32 v32, v143, v116
	v_mul_f32_e32 v33, v143, v117
	v_cvt_pk_bf16_f32 v32, v32, v33
	v_mul_f32_e32 v33, v143, v106
	v_mul_f32_e32 v34, v143, v107
	v_cvt_pk_bf16_f32 v33, v33, v34
	v_mul_f32_e32 v34, v144, v44
	v_mul_f32_e32 v35, v144, v45
	ds_write_b128 v156, v[30:33] offset:384
	v_cvt_pk_bf16_f32 v30, v44, v45
	v_cvt_pk_bf16_f32 v31, v42, v43
	v_cvt_pk_bf16_f32 v32, v36, v37
	v_cvt_pk_bf16_f32 v33, v46, v47
	v_cvt_pk_bf16_f32 v34, v34, v35
	v_mul_f32_e32 v35, v144, v42
	v_mul_f32_e32 v36, v144, v36
	v_mul_f32_e32 v37, v144, v37
	v_mul_f32_e32 v38, v144, v43
	v_cvt_pk_bf16_f32 v35, v35, v38
	v_cvt_pk_bf16_f32 v36, v36, v37
	v_mul_f32_e32 v37, v144, v46
	v_mul_f32_e32 v38, v144, v47
	v_cvt_pk_bf16_f32 v37, v37, v38
	ds_write_b128 v156, v[34:37] offset:448
	v_or_b32_e32 v36, s65, v152
	v_lshl_add_u64 v[34:35], s[46:47], 0, v[120:121]
	v_lshlrev_b32_e32 v36, 13, v36
	s_and_saveexec_b64 s[0:1], s[8:9]
	s_xor_b64 s[2:3], exec, s[0:1]
	s_cbranch_execz .LBB0_1379
	v_mov_b32_e32 v37, v121
	v_lshl_add_u64 v[38:39], v[34:35], 0, v[36:37]
	v_add_co_u32_e32 v38, vcc, 0xffffa000, v38
	s_nop 1
	v_addc_co_u32_e32 v39, vcc, -1, v39, vcc
	v_mov_b32_e32 v86, v228
	v_mov_b32_e32 v87, v229
	v_mov_b32_e32 v88, v230
	v_mov_b32_e32 v89, v231
	s_or_saveexec_b64 s[2:3], s[2:3]
	v_lshl_add_u64 v[38:39], s[44:45], 0, v[120:121]
	s_xor_b64 exec, exec, s[2:3]
	s_cbranch_execz .LBB0_1382
	s_branch .LBB0_1380

.LBB0_1625:
	s_ashr_i32 s29, s28, 31
	s_lshl_b64 s[0:1], s[28:29], 20
	s_add_u32 s30, s33, s0
	s_addc_u32 s31, s42, s1
	s_and_b64 s[0:1], s[6:7], exec
	s_cselect_b32 s11, s31, s39
	s_cselect_b32 s29, s30, s38
	s_ashr_i32 s27, s26, 31
	s_lshl_b64 s[0:1], s[26:27], 20
	s_add_u32 s34, s43, s0
	s_addc_u32 s35, s44, s1
	s_and_b64 s[0:1], s[6:7], exec
	s_cselect_b32 s27, s35, s3
	s_cselect_b32 s56, s34, s2
	s_add_u32 s38, s38, 0x80080
	s_addc_u32 s39, s39, 0
	s_add_u32 s57, s2, 0x100
	v_mov_b32_e32 v2, 0
	s_addc_u32 s58, s3, 0
	s_mov_b32 s59, -2
	s_waitcnt lgkmcnt(0)
	v_mov_b32_e32 v3, v2
	v_mov_b32_e32 v4, v2
	v_mov_b32_e32 v5, v2
	v_mov_b32_e32 v6, v2
	v_mov_b32_e32 v7, v2
	v_mov_b32_e32 v8, v2
	v_mov_b32_e32 v9, v2
	v_mov_b32_e32 v18, v2
	v_mov_b32_e32 v19, v2
	v_mov_b32_e32 v20, v2
	v_mov_b32_e32 v21, v2
	v_mov_b32_e32 v22, v2
	v_mov_b32_e32 v23, v2
	v_mov_b32_e32 v24, v2
	v_mov_b32_e32 v25, v2
	v_mov_b32_e32 v34, v2
	v_mov_b32_e32 v35, v2
	v_mov_b32_e32 v36, v2
	v_mov_b32_e32 v37, v2
	v_mov_b32_e32 v38, v2
	v_mov_b32_e32 v39, v2
	v_mov_b32_e32 v40, v2
	v_mov_b32_e32 v41, v2
	v_mov_b32_e32 v50, v2
	v_mov_b32_e32 v51, v2
	v_mov_b32_e32 v52, v2
	v_mov_b32_e32 v53, v2
	v_mov_b32_e32 v54, v2
	v_mov_b32_e32 v55, v2
	v_mov_b32_e32 v56, v2
	v_mov_b32_e32 v57, v2
	v_mov_b32_e32 v10, v2
	v_mov_b32_e32 v11, v2
	v_mov_b32_e32 v12, v2
	v_mov_b32_e32 v13, v2
	v_mov_b32_e32 v14, v2
	v_mov_b32_e32 v15, v2
	v_mov_b32_e32 v16, v2
	v_mov_b32_e32 v17, v2
	v_mov_b32_e32 v26, v2
	v_mov_b32_e32 v27, v2
	v_mov_b32_e32 v28, v2
	v_mov_b32_e32 v29, v2
	v_mov_b32_e32 v30, v2
	v_mov_b32_e32 v31, v2
	v_mov_b32_e32 v32, v2
	v_mov_b32_e32 v33, v2
	v_mov_b32_e32 v42, v2
	v_mov_b32_e32 v43, v2
	v_mov_b32_e32 v44, v2
	v_mov_b32_e32 v45, v2
	v_mov_b32_e32 v46, v2
	v_mov_b32_e32 v47, v2
	v_mov_b32_e32 v48, v2
	v_mov_b32_e32 v49, v2
	v_mov_b32_e32 v58, v2
	v_mov_b32_e32 v59, v2
	v_mov_b32_e32 v60, v2
	v_mov_b32_e32 v61, v2
	v_mov_b32_e32 v62, v2
	v_mov_b32_e32 v63, v2
	v_mov_b32_e32 v64, v2
	v_mov_b32_e32 v65, v2
	v_mov_b32_e32 v66, v2
	v_mov_b32_e32 v67, v2
	v_mov_b32_e32 v68, v2
	v_mov_b32_e32 v69, v2
	v_mov_b32_e32 v70, v2
	v_mov_b32_e32 v71, v2
	v_mov_b32_e32 v72, v2
	v_mov_b32_e32 v73, v2
	v_mov_b32_e32 v82, v2
	v_mov_b32_e32 v83, v2
	v_mov_b32_e32 v84, v2
	v_mov_b32_e32 v85, v2
	v_mov_b32_e32 v86, v2
	v_mov_b32_e32 v87, v2
	v_mov_b32_e32 v88, v2
	v_mov_b32_e32 v89, v2
	v_mov_b32_e32 v98, v2
	v_mov_b32_e32 v99, v2
	v_mov_b32_e32 v100, v2
	v_mov_b32_e32 v101, v2
	v_mov_b32_e32 v102, v2
	v_mov_b32_e32 v103, v2
	v_mov_b32_e32 v104, v2
	v_mov_b32_e32 v105, v2
	v_mov_b32_e32 v114, v2
	v_mov_b32_e32 v115, v2
	v_mov_b32_e32 v116, v2
	v_mov_b32_e32 v117, v2
	v_mov_b32_e32 v118, v2
	v_mov_b32_e32 v119, v2
	v_mov_b32_e32 v120, v2
	v_mov_b32_e32 v121, v2
	v_mov_b32_e32 v74, v2
	v_mov_b32_e32 v75, v2
	v_mov_b32_e32 v76, v2
	v_mov_b32_e32 v77, v2
	v_mov_b32_e32 v78, v2
	v_mov_b32_e32 v79, v2
	v_mov_b32_e32 v80, v2
	v_mov_b32_e32 v81, v2
	v_mov_b32_e32 v90, v2
	v_mov_b32_e32 v91, v2
	v_mov_b32_e32 v92, v2
	v_mov_b32_e32 v93, v2
	v_mov_b32_e32 v94, v2
	v_mov_b32_e32 v95, v2
	v_mov_b32_e32 v96, v2
	v_mov_b32_e32 v97, v2
	v_mov_b32_e32 v106, v2
	v_mov_b32_e32 v107, v2
	v_mov_b32_e32 v108, v2
	v_mov_b32_e32 v109, v2
	v_mov_b32_e32 v110, v2
	v_mov_b32_e32 v111, v2
	v_mov_b32_e32 v112, v2
	v_mov_b32_e32 v113, v2
	v_mov_b32_e32 v122, v2
	v_mov_b32_e32 v123, v2
	v_mov_b32_e32 v124, v2
	v_mov_b32_e32 v125, v2
	v_mov_b32_e32 v126, v2
	v_mov_b32_e32 v127, v2
	v_mov_b32_e32 v128, v2
	v_mov_b32_e32 v129, v2
	s_nop 0
	s_nop 0
	s_nop 0
	s_nop 0
	s_nop 0
.LBB0_1626:
	ds_read_b128 v[130:133], v186
	ds_read_b128 v[134:137], v186 offset:1024
	ds_read_b128 v[138:141], v186 offset:2048
	ds_read_b128 v[142:145], v186 offset:3072
	ds_read_b128 v[146:149], v187
	ds_read_b128 v[150:153], v187 offset:1024
	ds_read_b128 v[170:173], v187 offset:2048
	ds_read_b128 v[174:177], v187 offset:3072
	s_add_u32 s0, s38, 0xfff80080
	s_addc_u32 s1, s39, -1
	s_cmp_eq_u32 s59, 28
	s_cselect_b32 s41, s11, s1
	s_cselect_b32 s40, s29, s0
	s_cselect_b32 s3, s27, s58
	s_cselect_b32 s2, s56, s57
	v_lshl_add_u64 v[218:219], s[38:39], 0, v[162:163]
	s_add_i32 m0, s37, 0xc000
	ds_read_b128 v[178:181], v188
	ds_read_b128 v[190:193], v188 offset:1024
	ds_read_b128 v[194:197], v188 offset:2048
	ds_read_b128 v[198:201], v188 offset:3072
	ds_read_b128 v[202:205], v188 offset:4096
	ds_read_b128 v[206:209], v188 offset:5120
	ds_read_b128 v[210:213], v188 offset:6144
	ds_read_b128 v[214:217], v188 offset:7168
	global_load_lds_dwordx4 v[218:219], off
	v_lshl_add_u64 v[218:219], s[38:39], 0, v[164:165]
	s_add_i32 m0, s37, 0xe000
	s_nop 0
	global_load_lds_dwordx4 v[218:219], off
	s_waitcnt vmcnt(8)
	s_waitcnt lgkmcnt(0)
	s_barrier
	s_setprio 1
	s_waitcnt lgkmcnt(0)
	v_mfma_f32_16x16x32_bf16 v[126:129], v[130:133], v[178:181], v[126:129]
	v_mfma_f32_16x16x32_bf16 v[126:129], v[134:137], v[190:193], v[126:129]
	v_mfma_f32_16x16x32_bf16 v[122:125], v[138:141], v[178:181], v[122:125]
	v_mfma_f32_16x16x32_bf16 v[122:125], v[142:145], v[190:193], v[122:125]
	v_mfma_f32_16x16x32_bf16 v[110:113], v[130:133], v[194:197], v[110:113]
	v_mfma_f32_16x16x32_bf16 v[110:113], v[134:137], v[198:201], v[110:113]
	v_mfma_f32_16x16x32_bf16 v[106:109], v[138:141], v[194:197], v[106:109]
	v_mfma_f32_16x16x32_bf16 v[106:109], v[142:145], v[198:201], v[106:109]
	v_mfma_f32_16x16x32_bf16 v[94:97], v[130:133], v[202:205], v[94:97]
	v_mfma_f32_16x16x32_bf16 v[94:97], v[134:137], v[206:209], v[94:97]
	v_mfma_f32_16x16x32_bf16 v[90:93], v[138:141], v[202:205], v[90:93]
	v_mfma_f32_16x16x32_bf16 v[90:93], v[142:145], v[206:209], v[90:93]
	v_mfma_f32_16x16x32_bf16 v[78:81], v[130:133], v[210:213], v[78:81]
	v_mfma_f32_16x16x32_bf16 v[78:81], v[134:137], v[214:217], v[78:81]
	v_mfma_f32_16x16x32_bf16 v[74:77], v[138:141], v[210:213], v[74:77]
	v_mfma_f32_16x16x32_bf16 v[74:77], v[142:145], v[214:217], v[74:77]
	s_setprio 0
	s_setprio 1
	v_mfma_f32_16x16x32_bf16 v[118:121], v[146:149], v[178:181], v[118:121]
	v_mfma_f32_16x16x32_bf16 v[118:121], v[150:153], v[190:193], v[118:121]
	v_mfma_f32_16x16x32_bf16 v[114:117], v[170:173], v[178:181], v[114:117]
	v_mfma_f32_16x16x32_bf16 v[114:117], v[174:177], v[190:193], v[114:117]
	v_mfma_f32_16x16x32_bf16 v[102:105], v[146:149], v[194:197], v[102:105]
	v_mfma_f32_16x16x32_bf16 v[102:105], v[150:153], v[198:201], v[102:105]
	v_mfma_f32_16x16x32_bf16 v[98:101], v[170:173], v[194:197], v[98:101]
	v_mfma_f32_16x16x32_bf16 v[98:101], v[174:177], v[198:201], v[98:101]
	v_mfma_f32_16x16x32_bf16 v[86:89], v[146:149], v[202:205], v[86:89]
	v_mfma_f32_16x16x32_bf16 v[86:89], v[150:153], v[206:209], v[86:89]
	v_mfma_f32_16x16x32_bf16 v[82:85], v[170:173], v[202:205], v[82:85]
	v_mfma_f32_16x16x32_bf16 v[82:85], v[174:177], v[206:209], v[82:85]
	v_mfma_f32_16x16x32_bf16 v[70:73], v[146:149], v[210:213], v[70:73]
	v_mfma_f32_16x16x32_bf16 v[70:73], v[150:153], v[214:217], v[70:73]
	v_mfma_f32_16x16x32_bf16 v[66:69], v[170:173], v[210:213], v[66:69]
	v_mfma_f32_16x16x32_bf16 v[66:69], v[174:177], v[214:217], v[66:69]
	s_setprio 0
	s_barrier
	s_add_i32 s0, s54, s45
	v_lshl_add_u64 v[218:219], s[2:3], 0, v[156:157]
	s_mov_b32 m0, s0
	ds_read_b128 v[178:181], v188 offset:16384
	ds_read_b128 v[190:193], v188 offset:17408
	ds_read_b128 v[194:197], v188 offset:18432
	ds_read_b128 v[198:201], v188 offset:19456
	ds_read_b128 v[202:205], v188 offset:20480
	ds_read_b128 v[206:209], v188 offset:21504
	ds_read_b128 v[210:213], v188 offset:22528
	ds_read_b128 v[214:217], v188 offset:23552
	global_load_lds_dwordx4 v[218:219], off
	s_add_i32 m0, s0, 0x2000
	s_add_u32 s0, s2, 0x80000
	v_lshl_add_u64 v[220:221], s[2:3], 0, v[160:161]
	s_addc_u32 s1, s3, 0
	s_add_i32 s60, s55, s45
	global_load_lds_dwordx4 v[220:221], off
	v_lshl_add_u64 v[222:223], s[0:1], 0, v[156:157]
	s_mov_b32 m0, s60
	v_lshl_add_u64 v[224:225], s[40:41], 0, v[158:159]
	global_load_lds_dwordx4 v[222:223], off
	v_lshl_add_u64 v[222:223], s[0:1], 0, v[160:161]
	s_add_i32 m0, s60, 0x2000
	s_nop 0
	global_load_lds_dwordx4 v[222:223], off
	v_lshl_add_u64 v[222:223], s[40:41], 0, v[154:155]
	s_mov_b32 m0, s37
	s_nop 0
	global_load_lds_dwordx4 v[222:223], off
	s_mov_b32 m0, s46
	s_nop 0
	global_load_lds_dwordx4 v[224:225], off
	s_waitcnt vmcnt(8)
	s_waitcnt lgkmcnt(0)
	s_barrier
	s_setprio 1
	s_waitcnt lgkmcnt(0)
	v_mfma_f32_16x16x32_bf16 v[62:65], v[130:133], v[178:181], v[62:65]
	v_mfma_f32_16x16x32_bf16 v[62:65], v[134:137], v[190:193], v[62:65]
	v_mfma_f32_16x16x32_bf16 v[58:61], v[138:141], v[178:181], v[58:61]
	v_mfma_f32_16x16x32_bf16 v[58:61], v[142:145], v[190:193], v[58:61]
	v_mfma_f32_16x16x32_bf16 v[46:49], v[130:133], v[194:197], v[46:49]
	v_mfma_f32_16x16x32_bf16 v[46:49], v[134:137], v[198:201], v[46:49]
	v_mfma_f32_16x16x32_bf16 v[42:45], v[138:141], v[194:197], v[42:45]
	v_mfma_f32_16x16x32_bf16 v[42:45], v[142:145], v[198:201], v[42:45]
	v_mfma_f32_16x16x32_bf16 v[30:33], v[130:133], v[202:205], v[30:33]
	v_mfma_f32_16x16x32_bf16 v[30:33], v[134:137], v[206:209], v[30:33]
	v_mfma_f32_16x16x32_bf16 v[26:29], v[138:141], v[202:205], v[26:29]
	v_mfma_f32_16x16x32_bf16 v[26:29], v[142:145], v[206:209], v[26:29]
	v_mfma_f32_16x16x32_bf16 v[14:17], v[130:133], v[210:213], v[14:17]
	v_mfma_f32_16x16x32_bf16 v[14:17], v[134:137], v[214:217], v[14:17]
	v_mfma_f32_16x16x32_bf16 v[10:13], v[138:141], v[210:213], v[10:13]
	v_mfma_f32_16x16x32_bf16 v[10:13], v[142:145], v[214:217], v[10:13]
	s_setprio 0
	s_setprio 1
	v_mfma_f32_16x16x32_bf16 v[54:57], v[146:149], v[178:181], v[54:57]
	v_mfma_f32_16x16x32_bf16 v[54:57], v[150:153], v[190:193], v[54:57]
	v_mfma_f32_16x16x32_bf16 v[50:53], v[170:173], v[178:181], v[50:53]
	v_mfma_f32_16x16x32_bf16 v[50:53], v[174:177], v[190:193], v[50:53]
	v_mfma_f32_16x16x32_bf16 v[38:41], v[146:149], v[194:197], v[38:41]
	v_mfma_f32_16x16x32_bf16 v[38:41], v[150:153], v[198:201], v[38:41]
	v_mfma_f32_16x16x32_bf16 v[34:37], v[170:173], v[194:197], v[34:37]
	v_mfma_f32_16x16x32_bf16 v[34:37], v[174:177], v[198:201], v[34:37]
	v_mfma_f32_16x16x32_bf16 v[22:25], v[146:149], v[202:205], v[22:25]
	v_mfma_f32_16x16x32_bf16 v[22:25], v[150:153], v[206:209], v[22:25]
	v_mfma_f32_16x16x32_bf16 v[18:21], v[170:173], v[202:205], v[18:21]
	v_mfma_f32_16x16x32_bf16 v[18:21], v[174:177], v[206:209], v[18:21]
	v_mfma_f32_16x16x32_bf16 v[6:9], v[146:149], v[210:213], v[6:9]
	v_mfma_f32_16x16x32_bf16 v[6:9], v[150:153], v[214:217], v[6:9]
	v_mfma_f32_16x16x32_bf16 v[2:5], v[170:173], v[210:213], v[2:5]
	v_mfma_f32_16x16x32_bf16 v[2:5], v[174:177], v[214:217], v[2:5]
	s_setprio 0
	s_barrier
	s_add_i32 s60, 0, 0x18000
	s_add_i32 s61, 0, 0x1c000
	v_add_u32_e32 v142, s60, v182
	v_add_u32_e32 v174, s61, v182
	ds_read_b128 v[130:133], v142
	ds_read_b128 v[134:137], v142 offset:1024
	ds_read_b128 v[138:141], v142 offset:2048
	ds_read_b128 v[142:145], v142 offset:3072
	ds_read_b128 v[146:149], v174
	ds_read_b128 v[150:153], v174 offset:1024
	ds_read_b128 v[170:173], v174 offset:2048
	ds_read_b128 v[174:177], v174 offset:3072
	s_add_u32 s0, s40, 0x80000
	s_addc_u32 s1, s41, 0
	s_mov_b32 m0, s47
	v_lshl_add_u64 v[226:227], s[0:1], 0, v[154:155]
	ds_read_b128 v[178:181], v188 offset:32768
	ds_read_b128 v[190:193], v188 offset:33792
	ds_read_b128 v[194:197], v188 offset:34816
	ds_read_b128 v[198:201], v188 offset:35840
	ds_read_b128 v[202:205], v188 offset:36864
	ds_read_b128 v[206:209], v188 offset:37888
	ds_read_b128 v[210:213], v188 offset:38912
	ds_read_b128 v[214:217], v188 offset:39936
	global_load_lds_dwordx4 v[226:227], off
	v_lshl_add_u64 v[226:227], s[0:1], 0, v[158:159]
	s_mov_b32 m0, s48
	s_nop 0
	global_load_lds_dwordx4 v[226:227], off
	s_waitcnt vmcnt(8)
	s_waitcnt lgkmcnt(0)
	s_barrier
	s_setprio 1
	s_waitcnt lgkmcnt(0)
	v_mfma_f32_16x16x32_bf16 v[126:129], v[130:133], v[178:181], v[126:129]
	v_mfma_f32_16x16x32_bf16 v[126:129], v[134:137], v[190:193], v[126:129]
	v_mfma_f32_16x16x32_bf16 v[122:125], v[138:141], v[178:181], v[122:125]
	v_mfma_f32_16x16x32_bf16 v[122:125], v[142:145], v[190:193], v[122:125]
	v_mfma_f32_16x16x32_bf16 v[110:113], v[130:133], v[194:197], v[110:113]
	v_mfma_f32_16x16x32_bf16 v[110:113], v[134:137], v[198:201], v[110:113]
	v_mfma_f32_16x16x32_bf16 v[106:109], v[138:141], v[194:197], v[106:109]
	v_mfma_f32_16x16x32_bf16 v[106:109], v[142:145], v[198:201], v[106:109]
	v_mfma_f32_16x16x32_bf16 v[94:97], v[130:133], v[202:205], v[94:97]
	v_mfma_f32_16x16x32_bf16 v[94:97], v[134:137], v[206:209], v[94:97]
	v_mfma_f32_16x16x32_bf16 v[90:93], v[138:141], v[202:205], v[90:93]
	v_mfma_f32_16x16x32_bf16 v[90:93], v[142:145], v[206:209], v[90:93]
	v_mfma_f32_16x16x32_bf16 v[78:81], v[130:133], v[210:213], v[78:81]
	v_mfma_f32_16x16x32_bf16 v[78:81], v[134:137], v[214:217], v[78:81]
	v_mfma_f32_16x16x32_bf16 v[74:77], v[138:141], v[210:213], v[74:77]
	v_mfma_f32_16x16x32_bf16 v[74:77], v[142:145], v[214:217], v[74:77]
	s_setprio 0
	s_setprio 1
	v_mfma_f32_16x16x32_bf16 v[118:121], v[146:149], v[178:181], v[118:121]
	v_mfma_f32_16x16x32_bf16 v[118:121], v[150:153], v[190:193], v[118:121]
	v_mfma_f32_16x16x32_bf16 v[114:117], v[170:173], v[178:181], v[114:117]
	v_mfma_f32_16x16x32_bf16 v[114:117], v[174:177], v[190:193], v[114:117]
	v_mfma_f32_16x16x32_bf16 v[102:105], v[146:149], v[194:197], v[102:105]
	v_mfma_f32_16x16x32_bf16 v[102:105], v[150:153], v[198:201], v[102:105]
	v_mfma_f32_16x16x32_bf16 v[98:101], v[170:173], v[194:197], v[98:101]
	v_mfma_f32_16x16x32_bf16 v[98:101], v[174:177], v[198:201], v[98:101]
	v_mfma_f32_16x16x32_bf16 v[86:89], v[146:149], v[202:205], v[86:89]
	v_mfma_f32_16x16x32_bf16 v[86:89], v[150:153], v[206:209], v[86:89]
	v_mfma_f32_16x16x32_bf16 v[82:85], v[170:173], v[202:205], v[82:85]
	v_mfma_f32_16x16x32_bf16 v[82:85], v[174:177], v[206:209], v[82:85]
	v_mfma_f32_16x16x32_bf16 v[70:73], v[146:149], v[210:213], v[70:73]
	v_mfma_f32_16x16x32_bf16 v[70:73], v[150:153], v[214:217], v[70:73]
	v_mfma_f32_16x16x32_bf16 v[66:69], v[170:173], v[210:213], v[66:69]
	v_mfma_f32_16x16x32_bf16 v[66:69], v[174:177], v[214:217], v[66:69]
	s_setprio 0
	s_barrier
	s_add_i32 s0, s60, s45
	v_lshl_add_u64 v[218:219], v[218:219], 0, s[14:15]
	s_mov_b32 m0, s0
	ds_read_b128 v[178:181], v188 offset:49152
	ds_read_b128 v[190:193], v188 offset:50176
	ds_read_b128 v[194:197], v188 offset:51200
	ds_read_b128 v[198:201], v188 offset:52224
	ds_read_b128 v[202:205], v188 offset:53248
	ds_read_b128 v[206:209], v188 offset:54272
	ds_read_b128 v[210:213], v188 offset:55296
	ds_read_b128 v[214:217], v188 offset:56320
	global_load_lds_dwordx4 v[218:219], off
	s_add_i32 m0, s0, 0x2000
	s_add_u32 s0, s2, 0x80080
	v_lshl_add_u64 v[218:219], v[220:221], 0, s[14:15]
	s_addc_u32 s1, s3, 0
	s_add_i32 s2, s61, s45
	global_load_lds_dwordx4 v[218:219], off
	v_lshl_add_u64 v[218:219], s[0:1], 0, v[156:157]
	s_mov_b32 m0, s2
	s_nop 0
	global_load_lds_dwordx4 v[218:219], off
	v_lshl_add_u64 v[218:219], s[0:1], 0, v[160:161]
	s_add_i32 m0, s2, 0x2000
	s_nop 0
	global_load_lds_dwordx4 v[218:219], off
	v_lshl_add_u64 v[218:219], v[222:223], 0, s[14:15]
	s_mov_b32 m0, s50
	s_nop 0
	global_load_lds_dwordx4 v[218:219], off
	v_lshl_add_u64 v[218:219], v[224:225], 0, s[14:15]
	s_mov_b32 m0, s51
	s_nop 0
	global_load_lds_dwordx4 v[218:219], off
	s_waitcnt vmcnt(8)
	s_waitcnt lgkmcnt(0)
	s_barrier
	s_setprio 1
	s_waitcnt lgkmcnt(0)
	v_mfma_f32_16x16x32_bf16 v[62:65], v[130:133], v[178:181], v[62:65]
	v_mfma_f32_16x16x32_bf16 v[62:65], v[134:137], v[190:193], v[62:65]
	v_mfma_f32_16x16x32_bf16 v[58:61], v[138:141], v[178:181], v[58:61]
	v_mfma_f32_16x16x32_bf16 v[58:61], v[142:145], v[190:193], v[58:61]
	v_mfma_f32_16x16x32_bf16 v[46:49], v[130:133], v[194:197], v[46:49]
	v_mfma_f32_16x16x32_bf16 v[46:49], v[134:137], v[198:201], v[46:49]
	v_mfma_f32_16x16x32_bf16 v[42:45], v[138:141], v[194:197], v[42:45]
	v_mfma_f32_16x16x32_bf16 v[42:45], v[142:145], v[198:201], v[42:45]
	v_mfma_f32_16x16x32_bf16 v[30:33], v[130:133], v[202:205], v[30:33]
	v_mfma_f32_16x16x32_bf16 v[30:33], v[134:137], v[206:209], v[30:33]
	v_mfma_f32_16x16x32_bf16 v[26:29], v[138:141], v[202:205], v[26:29]
	v_mfma_f32_16x16x32_bf16 v[26:29], v[142:145], v[206:209], v[26:29]
	v_mfma_f32_16x16x32_bf16 v[14:17], v[130:133], v[210:213], v[14:17]
	v_mfma_f32_16x16x32_bf16 v[14:17], v[134:137], v[214:217], v[14:17]
	v_mfma_f32_16x16x32_bf16 v[10:13], v[138:141], v[210:213], v[10:13]
	v_mfma_f32_16x16x32_bf16 v[10:13], v[142:145], v[214:217], v[10:13]
	s_setprio 0
	s_setprio 1
	v_mfma_f32_16x16x32_bf16 v[54:57], v[146:149], v[178:181], v[54:57]
	v_mfma_f32_16x16x32_bf16 v[54:57], v[150:153], v[190:193], v[54:57]
	v_mfma_f32_16x16x32_bf16 v[50:53], v[170:173], v[178:181], v[50:53]
	v_mfma_f32_16x16x32_bf16 v[50:53], v[174:177], v[190:193], v[50:53]
	v_mfma_f32_16x16x32_bf16 v[38:41], v[146:149], v[194:197], v[38:41]
	v_mfma_f32_16x16x32_bf16 v[38:41], v[150:153], v[198:201], v[38:41]
	v_mfma_f32_16x16x32_bf16 v[34:37], v[170:173], v[194:197], v[34:37]
	v_mfma_f32_16x16x32_bf16 v[34:37], v[174:177], v[198:201], v[34:37]
	v_mfma_f32_16x16x32_bf16 v[22:25], v[146:149], v[202:205], v[22:25]
	v_mfma_f32_16x16x32_bf16 v[22:25], v[150:153], v[206:209], v[22:25]
	v_mfma_f32_16x16x32_bf16 v[18:21], v[170:173], v[202:205], v[18:21]
	v_mfma_f32_16x16x32_bf16 v[18:21], v[174:177], v[206:209], v[18:21]
	v_mfma_f32_16x16x32_bf16 v[6:9], v[146:149], v[210:213], v[6:9]
	v_mfma_f32_16x16x32_bf16 v[6:9], v[150:153], v[214:217], v[6:9]
	v_mfma_f32_16x16x32_bf16 v[2:5], v[170:173], v[210:213], v[2:5]
	v_mfma_f32_16x16x32_bf16 v[2:5], v[174:177], v[214:217], v[2:5]
	s_setprio 0
	s_barrier
	s_add_i32 s59, s59, 2
	s_add_u32 s38, s38, 0x100
	s_addc_u32 s39, s39, 0
	s_add_u32 s57, s57, 0x100
	s_addc_u32 s58, s58, 0
	s_cmp_gt_u32 s59, 29
	s_cbranch_scc0 .LBB0_1626
	s_and_b64 vcc, exec, s[16:17]
	s_cbranch_vccz .LBB0_1629
	s_barrier
